# group-barrier fast path: s_sleep 6 instead of s_sleep 1 between polls; on top of v65
# speedup vs baseline: 1.0033x; 1.0033x over previous
; __device__ __forceinline__ unsigned xb_ld(unsigned* p)              { return __hip_atomic_load(p, __ATOMIC_RELAXED, __HIP_MEMORY_SCOPE_AGENT); }
; __device__ __forceinline__ unsigned xb_add(unsigned* p, unsigned v) { return __hip_atomic_fetch_add(p, v, __ATOMIC_RELAXED, __HIP_MEMORY_SCOPE_AGENT); }
; #define XB_SPIN(cond, bar) do { unsigned _sp = 0; while (cond) { __builtin_amdgcn_s_sleep(1); \
;     if ((++_sp & 255u) == 0u) { if (xb_ld(&(bar)[XB_TMO])) break; if (_sp > XB_SPIN_CAP) { atomicAdd(&(bar)[XB_TMO], 1u); break; } } } } while (0)
; __device__ __forceinline__ void xcd_barrier(const XcdBarrier& b) {
;     ...
;             else XB_SPIN(xb_ld(&bar[XB_TOPGEN]) == tg, bar);
;             __builtin_amdgcn_fence(__ATOMIC_ACQUIRE, "agent");
;             xb_add(&bar[XB_XGEN(b.x)], 1u);
;             asm volatile("s_waitcnt vmcnt(0)" ::: "memory");
;         } else {
;             XB_SPIN(xb_ld(&bar[XB_XGEN(b.x)]) == gen, bar);
.Lgb_spin_g1:
	global_load_dword v3, v0, s[38:39] sc1
	s_waitcnt vmcnt(0)
	v_sub_u32_e32 v3, v3, v2
	v_cmp_gt_i32_e32 vcc, 0, v3
	s_cbranch_vccz .Lgb_done_g1
	s_sleep 6
	s_add_i32 s40, s40, 1
	s_cmp_lt_u32 s40, 0x100000
	s_cbranch_scc1 .Lgb_spin_g1
